# v11 + MLA loop: next-tile LDS-DMA issue interleaved into the QK MFMA shadow (separate plain path for last tiles / skipped waves)
# speedup vs baseline: 1.0068x; 1.0051x over previous
; #define MFMA32(a, b, c) __builtin_amdgcn_mfma_f32_32x32x16_bf16((a), (b), (c), 0, 0, 0)
; template <int DQK, int DV, int MODE, int VR> ...
;     ...
;                 {
;                     constexpr int NS = 2 * NKS;
;                     const unsigned char* kb0 = Kl + pirow * KSTR + 16 * hi;
;     ...
;                     bf16x8 af[3]; af[0] = AT_KF(0); af[1] = AT_KF(1);
; #pragma unroll
;                     for (int i = 0; i < NS; ++i) { if (i + 2 < NS) af[(i + 2) % 3] = AT_KF(i + 2); p[i & 1] = MFMA32(af[i % 3], qf[i >> 1], p[i & 1]); }
;     ...
;                     __builtin_amdgcn_sched_group_barrier(0x100, 2, 0);
; #pragma unroll
;                     for (int i = 0; i < NS - 2; ++i) { __builtin_amdgcn_sched_group_barrier(0x100, 1, 0); __builtin_amdgcn_sched_group_barrier(0x8, 1, 0); }
;                     __builtin_amdgcn_sched_group_barrier(0x8, 2, 0);
;                 }
.LBB0_735:
	s_add_i32 s4, s78, 0x42
	s_cmp_ge_u32 s4, s81
	s_cselect_b64 s[60:61], -1, 0
	s_sub_i32 s4, s79, 63
	s_cmp_gt_i32 s4, s63
	s_cbranch_scc1 .Lmla_skipwave
	s_and_b64 vcc, exec, s[60:61]
	s_cbranch_vccnz .Lmla_qk_plain
	s_mul_hi_u32 s4, s76, 0xaaaaaaab
	s_lshr_b32 s30, s4, 1
	s_mul_i32 s30, s30, 0x20700
	v_subrev_u32_e32 v0, s30, v174
	v_add_u32_e32 v180, s64, v176
	v_add_u32_e32 v0, v180, v0
	ds_read_b128 v[66:69], v0
	ds_read_b128 v[70:73], v0 offset:12800
	ds_read_b128 v[184:187], v0 offset:32
	s_waitcnt lgkmcnt(2)
	v_mfma_f32_32x32x16_bf16 v[82:97], v[66:69], v[98:101], 0
	ds_read_b128 v[188:191], v0 offset:12832
	s_mul_hi_u32 s4, s62, 0xaaaaaaab
	s_lshr_b32 s4, s4, 1
	s_mul_i32 s4, s4, 0x20700
	s_sub_i32 s4, s67, s4
	s_waitcnt lgkmcnt(2)
	v_mfma_f32_32x32x16_bf16 v[66:81], v[70:73], v[98:101], 0
	ds_read_b128 v[204:207], v0 offset:64
	s_add_i32 s4, s64, s4
	s_add_i32 s5, s4, 0x15a00
	s_and_b64 vcc, s[58:59], exec
	s_cselect_b32 s5, s5, s66
	s_waitcnt lgkmcnt(2)
	v_mfma_f32_32x32x16_bf16 v[82:97], v[184:187], v[102:105], v[82:97]
	ds_read_b128 v[184:187], v0 offset:12864
	v_lshl_add_u64 v[210:211], s[92:93], 0, v[146:147]
	v_mov_b32_e32 v212, s0
	v_mov_b32_e32 v213, s1
	s_add_i32 m0, s5, 16
	s_waitcnt lgkmcnt(2)
	v_mfma_f32_32x32x16_bf16 v[66:81], v[188:191], v[102:105], v[66:81]
	ds_read_b128 v[188:191], v0 offset:96
	s_add_i32 s5, s4, 0x17a00
	v_lshl_add_u64 v[208:209], s[92:93], 0, v[158:159]
	v_cndmask_b32_e64 v210, v212, v210, s[18:19]
	v_cndmask_b32_e64 v211, v213, v211, s[18:19]
	s_waitcnt lgkmcnt(2)
	v_mfma_f32_32x32x16_bf16 v[82:97], v[204:207], v[106:109], v[82:97]
	ds_read_b128 v[204:207], v0 offset:12896
	s_and_b64 vcc, s[56:57], exec
	v_cndmask_b32_e64 v209, v211, v209, s[6:7]
	v_cndmask_b32_e64 v208, v210, v208, s[6:7]
	s_cselect_b32 s5, s5, s84
	s_waitcnt lgkmcnt(2)
	v_mfma_f32_32x32x16_bf16 v[66:81], v[184:187], v[106:109], v[66:81]
	ds_read_b128 v[184:187], v0 offset:128
	global_load_lds_dwordx4 v[208:209], off
	v_lshl_add_u64 v[210:211], s[92:93], 0, v[148:149]
	s_add_i32 m0, s5, 16
	s_add_i32 s5, s4, 0x19a00
	s_waitcnt lgkmcnt(2)
	v_mfma_f32_32x32x16_bf16 v[82:97], v[188:191], v[110:113], v[82:97]
	ds_read_b128 v[188:191], v0 offset:12928
	v_lshl_add_u64 v[208:209], s[92:93], 0, v[160:161]
	v_cndmask_b32_e64 v210, v212, v210, s[20:21]
	v_cndmask_b32_e64 v211, v213, v211, s[20:21]
	s_and_b64 vcc, s[54:55], exec
	s_waitcnt lgkmcnt(2)
	v_mfma_f32_32x32x16_bf16 v[66:81], v[204:207], v[110:113], v[66:81]
	ds_read_b128 v[204:207], v0 offset:160
	v_cndmask_b32_e64 v209, v211, v209, s[8:9]
	v_cndmask_b32_e64 v208, v210, v208, s[8:9]
	s_cselect_b32 s5, s5, s85
	global_load_lds_dwordx4 v[208:209], off
	s_waitcnt lgkmcnt(2)
	v_mfma_f32_32x32x16_bf16 v[82:97], v[184:187], v[114:117], v[82:97]
	ds_read_b128 v[184:187], v0 offset:12960
	v_lshl_add_u64 v[210:211], s[92:93], 0, v[150:151]
	s_add_i32 m0, s5, 16
	s_add_i32 s5, s4, 0x1ba00
	v_lshl_add_u64 v[208:209], s[92:93], 0, v[162:163]
	s_waitcnt lgkmcnt(2)
	v_mfma_f32_32x32x16_bf16 v[66:81], v[188:191], v[114:117], v[66:81]
	ds_read_b128 v[188:191], v0 offset:192
	v_cndmask_b32_e64 v210, v212, v210, s[22:23]
	v_cndmask_b32_e64 v211, v213, v211, s[22:23]
	s_and_b64 vcc, s[52:53], exec
	v_cndmask_b32_e64 v209, v211, v209, s[10:11]
	s_waitcnt lgkmcnt(2)
	v_mfma_f32_32x32x16_bf16 v[82:97], v[204:207], v[118:121], v[82:97]
	ds_read_b128 v[204:207], v0 offset:12992
	v_cndmask_b32_e64 v208, v210, v208, s[10:11]
	s_cselect_b32 s5, s5, s94
	global_load_lds_dwordx4 v[208:209], off
	v_lshl_add_u64 v[210:211], s[92:93], 0, v[152:153]
	s_waitcnt lgkmcnt(2)
	v_mfma_f32_32x32x16_bf16 v[66:81], v[184:187], v[118:121], v[66:81]
	ds_read_b128 v[184:187], v0 offset:224
	s_add_i32 m0, s5, 16
	s_add_i32 s5, s4, 0x1da00
	v_lshl_add_u64 v[208:209], s[92:93], 0, v[164:165]
	v_cndmask_b32_e64 v210, v212, v210, s[24:25]
	s_waitcnt lgkmcnt(2)
	v_mfma_f32_32x32x16_bf16 v[82:97], v[188:191], v[122:125], v[82:97]
	ds_read_b128 v[188:191], v0 offset:13024
	v_cndmask_b32_e64 v211, v213, v211, s[24:25]
	s_and_b64 vcc, s[34:35], exec
	v_cndmask_b32_e64 v209, v211, v209, s[12:13]
	v_cndmask_b32_e64 v208, v210, v208, s[12:13]
	s_waitcnt lgkmcnt(2)
	v_mfma_f32_32x32x16_bf16 v[66:81], v[204:207], v[122:125], v[66:81]
	ds_read_b128 v[204:207], v0 offset:256
	v_lshl_add_u64 v[210:211], s[92:93], 0, v[154:155]
	s_cselect_b32 s5, s5, s95
	global_load_lds_dwordx4 v[208:209], off
	v_lshl_add_u64 v[208:209], s[92:93], 0, v[166:167]
	s_waitcnt lgkmcnt(2)
	v_mfma_f32_32x32x16_bf16 v[82:97], v[184:187], v[126:129], v[82:97]
	ds_read_b128 v[184:187], v0 offset:13056
	v_cndmask_b32_e64 v210, v212, v210, s[26:27]
	v_cndmask_b32_e64 v211, v213, v211, s[26:27]
	s_add_i32 m0, s5, 16
	s_add_i32 s4, s4, 0x1fa00
	s_waitcnt lgkmcnt(2)
	v_mfma_f32_32x32x16_bf16 v[66:81], v[188:191], v[126:129], v[66:81]
	ds_read_b128 v[188:191], v0 offset:288
	v_cndmask_b32_e64 v209, v211, v209, s[14:15]
	v_cndmask_b32_e64 v208, v210, v208, s[14:15]
	v_lshl_add_u64 v[210:211], s[92:93], 0, v[156:157]
	s_and_b64 vcc, s[2:3], exec
	s_waitcnt lgkmcnt(2)
	v_mfma_f32_32x32x16_bf16 v[82:97], v[204:207], v[130:133], v[82:97]
	ds_read_b128 v[204:207], v0 offset:13088
	global_load_lds_dwordx4 v[208:209], off
	v_lshl_add_u64 v[208:209], s[92:93], 0, v[168:169]
	v_cndmask_b32_e64 v212, v212, v210, s[28:29]
	v_cndmask_b32_e64 v210, v213, v211, s[28:29]
	s_waitcnt lgkmcnt(2)
	v_mfma_f32_32x32x16_bf16 v[66:81], v[184:187], v[130:133], v[66:81]
	ds_read_b128 v[184:187], v0 offset:320
	s_cselect_b32 s4, s4, s80
	v_cndmask_b32_e64 v209, v210, v209, s[16:17]
	v_cndmask_b32_e64 v208, v212, v208, s[16:17]
	s_add_i32 m0, s4, 16
	s_waitcnt lgkmcnt(2)
	v_mfma_f32_32x32x16_bf16 v[82:97], v[188:191], v[134:137], v[82:97]
	ds_read_b128 v[188:191], v0 offset:13120
	s_nop 0
	global_load_lds_dwordx4 v[208:209], off
	s_waitcnt lgkmcnt(2)
	v_mfma_f32_32x32x16_bf16 v[66:81], v[204:207], v[134:137], v[66:81]
	ds_read_b128 v[204:207], v0 offset:352
	s_waitcnt lgkmcnt(2)
	v_mfma_f32_32x32x16_bf16 v[82:97], v[184:187], v[138:141], v[82:97]
	ds_read_b128 v[184:187], v0 offset:13152
	s_waitcnt lgkmcnt(2)
	v_mfma_f32_32x32x16_bf16 v[66:81], v[188:191], v[138:141], v[66:81]
	s_waitcnt lgkmcnt(1)
	v_mfma_f32_32x32x16_bf16 v[82:97], v[204:207], v[142:145], v[82:97]
	s_waitcnt lgkmcnt(0)
	v_mfma_f32_32x32x16_bf16 v[66:81], v[184:187], v[142:145], v[66:81]
	s_branch .Lmla_qk_done
; #define MFMA32(a, b, c) __builtin_amdgcn_mfma_f32_32x32x16_bf16((a), (b), (c), 0, 0, 0)
; template <int DQK, int DV, int MODE, int VR> ...
;     ...
;                 {
;                     constexpr int NS = 2 * NKS;
;                     const unsigned char* kb0 = Kl + pirow * KSTR + 16 * hi;
;     ...
;                     bf16x8 af[3]; af[0] = AT_KF(0); af[1] = AT_KF(1);
; #pragma unroll
;                     for (int i = 0; i < NS; ++i) { if (i + 2 < NS) af[(i + 2) % 3] = AT_KF(i + 2); p[i & 1] = MFMA32(af[i % 3], qf[i >> 1], p[i & 1]); }
;     ...
;                     __builtin_amdgcn_sched_group_barrier(0x100, 2, 0);
; #pragma unroll
;                     for (int i = 0; i < NS - 2; ++i) { __builtin_amdgcn_sched_group_barrier(0x100, 1, 0); __builtin_amdgcn_sched_group_barrier(0x8, 1, 0); }
;                     __builtin_amdgcn_sched_group_barrier(0x8, 2, 0);
;                 }
.Lmla_skipwave:
	s_and_b64 vcc, exec, s[60:61]
	s_cbranch_vccnz .LBB0_743
	s_mul_hi_u32 s4, s62, 0xaaaaaaab
	s_lshr_b32 s4, s4, 1
	s_mul_i32 s4, s4, 0x20700
	s_sub_i32 s4, s67, s4
	s_add_i32 s4, s64, s4
	s_add_i32 s5, s4, 0x15a00
	s_and_b64 s[30:31], s[58:59], exec
	s_cselect_b32 s5, s5, s66
	v_lshl_add_u64 v[68:69], s[92:93], 0, v[146:147]
	v_mov_b32_e32 v0, s0
	v_mov_b32_e32 v70, s1
	s_add_i32 m0, s5, 16
	s_add_i32 s5, s4, 0x17a00
	v_lshl_add_u64 v[66:67], s[92:93], 0, v[158:159]
	v_cndmask_b32_e64 v68, v0, v68, s[18:19]
	v_cndmask_b32_e64 v69, v70, v69, s[18:19]
	s_and_b64 s[30:31], s[56:57], exec
	v_cndmask_b32_e64 v67, v69, v67, s[6:7]
	v_cndmask_b32_e64 v66, v68, v66, s[6:7]
	s_cselect_b32 s5, s5, s84
	global_load_lds_dwordx4 v[66:67], off
	v_lshl_add_u64 v[68:69], s[92:93], 0, v[148:149]
	s_add_i32 m0, s5, 16
	s_add_i32 s5, s4, 0x19a00
	v_lshl_add_u64 v[66:67], s[92:93], 0, v[160:161]
	v_cndmask_b32_e64 v68, v0, v68, s[20:21]
	v_cndmask_b32_e64 v69, v70, v69, s[20:21]
	s_and_b64 s[30:31], s[54:55], exec
	v_cndmask_b32_e64 v67, v69, v67, s[8:9]
	v_cndmask_b32_e64 v66, v68, v66, s[8:9]
	s_cselect_b32 s5, s5, s85
	global_load_lds_dwordx4 v[66:67], off
	v_lshl_add_u64 v[68:69], s[92:93], 0, v[150:151]
	s_add_i32 m0, s5, 16
	s_add_i32 s5, s4, 0x1ba00
	v_lshl_add_u64 v[66:67], s[92:93], 0, v[162:163]
	v_cndmask_b32_e64 v68, v0, v68, s[22:23]
	v_cndmask_b32_e64 v69, v70, v69, s[22:23]
	s_and_b64 s[30:31], s[52:53], exec
	v_cndmask_b32_e64 v67, v69, v67, s[10:11]
	v_cndmask_b32_e64 v66, v68, v66, s[10:11]
	s_cselect_b32 s5, s5, s94
	global_load_lds_dwordx4 v[66:67], off
	v_lshl_add_u64 v[68:69], s[92:93], 0, v[152:153]
	s_add_i32 m0, s5, 16
	s_add_i32 s5, s4, 0x1da00
	v_lshl_add_u64 v[66:67], s[92:93], 0, v[164:165]
	v_cndmask_b32_e64 v68, v0, v68, s[24:25]
	v_cndmask_b32_e64 v69, v70, v69, s[24:25]
	s_and_b64 s[30:31], s[34:35], exec
	v_cndmask_b32_e64 v67, v69, v67, s[12:13]
	v_cndmask_b32_e64 v66, v68, v66, s[12:13]
	v_lshl_add_u64 v[68:69], s[92:93], 0, v[154:155]
	s_cselect_b32 s5, s5, s95
	global_load_lds_dwordx4 v[66:67], off
	v_lshl_add_u64 v[66:67], s[92:93], 0, v[166:167]
	v_cndmask_b32_e64 v68, v0, v68, s[26:27]
	v_cndmask_b32_e64 v69, v70, v69, s[26:27]
	s_add_i32 m0, s5, 16
	s_add_i32 s4, s4, 0x1fa00
	v_cndmask_b32_e64 v67, v69, v67, s[14:15]
	v_cndmask_b32_e64 v66, v68, v66, s[14:15]
	v_lshl_add_u64 v[68:69], s[92:93], 0, v[156:157]
	s_and_b64 s[30:31], s[2:3], exec
	global_load_lds_dwordx4 v[66:67], off
	v_lshl_add_u64 v[66:67], s[92:93], 0, v[168:169]
	v_cndmask_b32_e64 v0, v0, v68, s[28:29]
	v_cndmask_b32_e64 v68, v70, v69, s[28:29]
	s_cselect_b32 s4, s4, s80
	v_cndmask_b32_e64 v67, v68, v67, s[16:17]
	v_cndmask_b32_e64 v66, v0, v66, s[16:17]
	s_add_i32 m0, s4, 16
	s_nop 0
	global_load_lds_dwordx4 v[66:67], off
	s_branch .LBB0_743
.Lmla_qk_plain:
	s_mul_hi_u32 s4, s76, 0xaaaaaaab
	s_lshr_b32 s30, s4, 1
	s_mul_i32 s30, s30, 0x20700
	v_subrev_u32_e32 v0, s30, v174
	v_add_u32_e32 v180, s64, v176
	v_add_u32_e32 v0, v180, v0
	ds_read_b128 v[66:69], v0
	ds_read_b128 v[70:73], v0 offset:12800
	ds_read_b128 v[184:187], v0 offset:32
	s_waitcnt lgkmcnt(2)
	v_mfma_f32_32x32x16_bf16 v[82:97], v[66:69], v[98:101], 0
	ds_read_b128 v[188:191], v0 offset:12832
	s_waitcnt lgkmcnt(2)
	v_mfma_f32_32x32x16_bf16 v[66:81], v[70:73], v[98:101], 0
	ds_read_b128 v[204:207], v0 offset:64
	s_waitcnt lgkmcnt(2)
	v_mfma_f32_32x32x16_bf16 v[82:97], v[184:187], v[102:105], v[82:97]
	ds_read_b128 v[184:187], v0 offset:12864
	s_waitcnt lgkmcnt(2)
	v_mfma_f32_32x32x16_bf16 v[66:81], v[188:191], v[102:105], v[66:81]
	ds_read_b128 v[188:191], v0 offset:96
	s_waitcnt lgkmcnt(2)
	v_mfma_f32_32x32x16_bf16 v[82:97], v[204:207], v[106:109], v[82:97]
	ds_read_b128 v[204:207], v0 offset:12896
	s_waitcnt lgkmcnt(2)
	v_mfma_f32_32x32x16_bf16 v[66:81], v[184:187], v[106:109], v[66:81]
	ds_read_b128 v[184:187], v0 offset:128
	s_waitcnt lgkmcnt(2)
	v_mfma_f32_32x32x16_bf16 v[82:97], v[188:191], v[110:113], v[82:97]
	ds_read_b128 v[188:191], v0 offset:12928
	s_waitcnt lgkmcnt(2)
	v_mfma_f32_32x32x16_bf16 v[66:81], v[204:207], v[110:113], v[66:81]
	ds_read_b128 v[204:207], v0 offset:160
	s_waitcnt lgkmcnt(2)
	v_mfma_f32_32x32x16_bf16 v[82:97], v[184:187], v[114:117], v[82:97]
	ds_read_b128 v[184:187], v0 offset:12960
	s_waitcnt lgkmcnt(2)
	v_mfma_f32_32x32x16_bf16 v[66:81], v[188:191], v[114:117], v[66:81]
	ds_read_b128 v[188:191], v0 offset:192
	s_waitcnt lgkmcnt(2)
	v_mfma_f32_32x32x16_bf16 v[82:97], v[204:207], v[118:121], v[82:97]
	ds_read_b128 v[204:207], v0 offset:12992
	s_waitcnt lgkmcnt(2)
	v_mfma_f32_32x32x16_bf16 v[66:81], v[184:187], v[118:121], v[66:81]
	ds_read_b128 v[184:187], v0 offset:224
	s_waitcnt lgkmcnt(2)
	v_mfma_f32_32x32x16_bf16 v[82:97], v[188:191], v[122:125], v[82:97]
	ds_read_b128 v[188:191], v0 offset:13024
	s_waitcnt lgkmcnt(2)
	v_mfma_f32_32x32x16_bf16 v[66:81], v[204:207], v[122:125], v[66:81]
	ds_read_b128 v[204:207], v0 offset:256
	s_waitcnt lgkmcnt(2)
	v_mfma_f32_32x32x16_bf16 v[82:97], v[184:187], v[126:129], v[82:97]
	ds_read_b128 v[184:187], v0 offset:13056
	s_waitcnt lgkmcnt(2)
	v_mfma_f32_32x32x16_bf16 v[66:81], v[188:191], v[126:129], v[66:81]
	ds_read_b128 v[188:191], v0 offset:288
	s_waitcnt lgkmcnt(2)
	v_mfma_f32_32x32x16_bf16 v[82:97], v[204:207], v[130:133], v[82:97]
	ds_read_b128 v[204:207], v0 offset:13088
	s_waitcnt lgkmcnt(2)
	v_mfma_f32_32x32x16_bf16 v[66:81], v[184:187], v[130:133], v[66:81]
	ds_read_b128 v[184:187], v0 offset:320
	s_waitcnt lgkmcnt(2)
	v_mfma_f32_32x32x16_bf16 v[82:97], v[188:191], v[134:137], v[82:97]
	ds_read_b128 v[188:191], v0 offset:13120
	s_waitcnt lgkmcnt(2)
	v_mfma_f32_32x32x16_bf16 v[66:81], v[204:207], v[134:137], v[66:81]
	ds_read_b128 v[204:207], v0 offset:352
	s_waitcnt lgkmcnt(2)
	v_mfma_f32_32x32x16_bf16 v[82:97], v[184:187], v[138:141], v[82:97]
	ds_read_b128 v[184:187], v0 offset:13152
	s_waitcnt lgkmcnt(2)
	v_mfma_f32_32x32x16_bf16 v[66:81], v[188:191], v[138:141], v[66:81]
	s_waitcnt lgkmcnt(1)
	v_mfma_f32_32x32x16_bf16 v[82:97], v[204:207], v[142:145], v[82:97]
	s_waitcnt lgkmcnt(0)
	v_mfma_f32_32x32x16_bf16 v[66:81], v[184:187], v[142:145], v[66:81]
; template <int DQK, int DV, int MODE, int VR> ...
;     ...
;                 if (diag) {
; #pragma unroll
;                     for (int kb = 0; kb < 2; ++kb)
; #pragma unroll
;                         for (int r = 0; r < 16; ++r) { const int kv = kv0 + 32 * kb + 16 * (r >> 3) + 8 * hi + (r & 7); if (kv > t) p[kb][r] = -INFINITY; }
;                 }
.Lmla_qk_done:
	s_cmp_le_i32 s79, s86
	s_cbranch_scc1 .LBB0_740
	v_add_u32_e32 v0, s79, v173
	v_subrev_u32_e32 v177, 63, v0
	v_cmp_gt_i32_e32 vcc, v177, v172
	s_nop 6
	v_cndmask_b32_e32 v183, v82, v227, vcc
	v_cmp_lt_i32_e32 vcc, v177, v172
	v_subrev_u32_e32 v177, 61, v0
	s_nop 0
	v_cndmask_b32_e32 v82, v183, v82, vcc
	v_cndmask_b32_e32 v83, v227, v83, vcc
	v_cmp_le_i32_e32 vcc, v177, v172
	v_subrev_u32_e32 v177, 60, v0
	s_nop 0
	v_cndmask_b32_e32 v84, v227, v84, vcc
	v_cmp_le_i32_e32 vcc, v177, v172
	v_subrev_u32_e32 v177, 59, v0
	s_nop 0
	v_cndmask_b32_e32 v85, v227, v85, vcc
	v_cmp_le_i32_e32 vcc, v177, v172
	v_subrev_u32_e32 v177, 58, v0
	s_nop 0
	v_cndmask_b32_e32 v86, v227, v86, vcc
	v_cmp_le_i32_e32 vcc, v177, v172
	v_subrev_u32_e32 v177, 57, v0
	s_nop 0
	v_cndmask_b32_e32 v87, v227, v87, vcc
	v_cmp_le_i32_e32 vcc, v177, v172
	v_subrev_u32_e32 v177, 56, v0
	s_nop 0
	v_cndmask_b32_e32 v88, v227, v88, vcc
	v_cmp_le_i32_e32 vcc, v177, v172
	v_subrev_u32_e32 v177, 47, v0
	s_nop 0
	v_cndmask_b32_e32 v89, v227, v89, vcc
	v_cmp_le_i32_e32 vcc, v177, v172
	v_subrev_u32_e32 v177, 46, v0
	s_nop 0
	v_cndmask_b32_e32 v90, v227, v90, vcc
	v_cmp_le_i32_e32 vcc, v177, v172
	v_subrev_u32_e32 v177, 45, v0
	s_nop 0
	v_cndmask_b32_e32 v91, v227, v91, vcc
	v_cmp_le_i32_e32 vcc, v177, v172
	v_subrev_u32_e32 v177, 44, v0
	s_nop 0
	v_cndmask_b32_e32 v92, v227, v92, vcc
	v_cmp_le_i32_e32 vcc, v177, v172
	v_subrev_u32_e32 v177, 43, v0
	s_nop 0
	v_cndmask_b32_e32 v93, v227, v93, vcc
	v_cmp_le_i32_e32 vcc, v177, v172
	v_subrev_u32_e32 v177, 42, v0
	s_nop 0
	v_cndmask_b32_e32 v94, v227, v94, vcc
	v_cmp_le_i32_e32 vcc, v177, v172
	v_subrev_u32_e32 v177, 41, v0
	s_nop 0
	v_cndmask_b32_e32 v95, v227, v95, vcc
	v_cmp_le_i32_e32 vcc, v177, v172
	v_subrev_u32_e32 v177, 40, v0
	s_nop 0
	v_cndmask_b32_e32 v96, v227, v96, vcc
	v_cmp_le_i32_e32 vcc, v177, v172
	v_subrev_u32_e32 v177, 31, v0
	s_nop 0
	v_cndmask_b32_e32 v97, v227, v97, vcc
	v_cmp_le_i32_e32 vcc, v177, v172
	v_subrev_u32_e32 v177, 30, v0
	s_nop 0
	v_cndmask_b32_e32 v66, v227, v66, vcc
	v_cmp_le_i32_e32 vcc, v177, v172
	v_subrev_u32_e32 v177, 29, v0
	s_nop 0
	v_cndmask_b32_e32 v67, v227, v67, vcc
	v_cmp_le_i32_e32 vcc, v177, v172
	v_subrev_u32_e32 v177, 28, v0
	s_nop 0
	v_cndmask_b32_e32 v68, v227, v68, vcc
	v_cmp_le_i32_e32 vcc, v177, v172
	v_subrev_u32_e32 v177, 27, v0
	s_nop 0
	v_cndmask_b32_e32 v69, v227, v69, vcc
	v_cmp_le_i32_e32 vcc, v177, v172
	v_subrev_u32_e32 v177, 26, v0
	s_nop 0
	v_cndmask_b32_e32 v70, v227, v70, vcc
	v_cmp_le_i32_e32 vcc, v177, v172
	v_subrev_u32_e32 v177, 25, v0
	s_nop 0
	v_cndmask_b32_e32 v71, v227, v71, vcc
	v_cmp_le_i32_e32 vcc, v177, v172
	v_subrev_u32_e32 v177, 24, v0
	s_nop 0
	v_cndmask_b32_e32 v72, v227, v72, vcc
	v_cmp_le_i32_e32 vcc, v177, v172
	v_add_u32_e32 v177, -15, v0
	s_nop 0
	v_cndmask_b32_e32 v73, v227, v73, vcc
	v_cmp_le_i32_e32 vcc, v177, v172
	v_add_u32_e32 v177, -14, v0
	s_nop 0
	v_cndmask_b32_e32 v74, v227, v74, vcc
	v_cmp_le_i32_e32 vcc, v177, v172
	v_add_u32_e32 v177, -13, v0
	s_nop 0
	v_cndmask_b32_e32 v75, v227, v75, vcc
	v_cmp_le_i32_e32 vcc, v177, v172
	v_add_u32_e32 v177, -12, v0
	s_nop 0
	v_cndmask_b32_e32 v76, v227, v76, vcc
	v_cmp_le_i32_e32 vcc, v177, v172
	v_add_u32_e32 v177, -11, v0
	s_nop 0
	v_cndmask_b32_e32 v77, v227, v77, vcc
	v_cmp_le_i32_e32 vcc, v177, v172
	v_add_u32_e32 v177, -10, v0
	s_nop 0
	v_cndmask_b32_e32 v78, v227, v78, vcc
	v_cmp_le_i32_e32 vcc, v177, v172
	v_add_u32_e32 v177, -9, v0
	v_add_u32_e32 v0, -8, v0
	v_cndmask_b32_e32 v79, v227, v79, vcc
	v_cmp_le_i32_e32 vcc, v177, v172
	s_nop 1
	v_cndmask_b32_e32 v80, v227, v80, vcc
	v_cmp_le_i32_e32 vcc, v0, v172
	s_nop 1
	v_cndmask_b32_e32 v81, v227, v81, vcc
